# GLA scan: prompt items dealt only to workgroups that host no long sample item
# speedup vs baseline: 1.0097x; 1.0097x over previous
.LBB0_560:
	s_andn2_b64 vcc, exec, s[0:1]
	s_mov_b32 s27, 0
	s_cbranch_vccnz .LBB0_562
	s_cmpk_lt_i32 s3, 0x80
	s_cselect_b64 vcc, -1, 0
	s_and_b64 s[4:5], vcc, exec
	v_mov_b32_e32 v6, s3
	s_cselect_b32 s27, 0x61, 0
	s_lshl_b32 s3, s3, 1
	v_ashrrev_i32_e32 v5, 8, v4
	s_movk_i32 s0, 0x100
	s_addk_i32 s3, 0xff00
	v_cmp_gt_u32_e64 s[0:1], s0, v4
	v_add_u32_e32 v4, s3, v5
	s_lshl_b32 s2, s2, 1
	v_cndmask_b32_e32 v4, v4, v6, vcc
	s_addk_i32 s2, 0xff00
	v_add_u32_e32 v4, 0x80, v4
	v_mov_b32_e32 v7, 0x100000
	v_cndmask_b32_e32 v4, v4, v7, vcc
	v_mov_b32_e32 v5, s2
	s_and_b64 vcc, vcc, s[0:1]
	v_mov_b32_e32 v7, 0x100000
	v_cndmask_b32_e32 v141, v5, v7, vcc
	v_cndmask_b32_e32 v37, v4, v6, vcc
